# SB unit top: prefetched K0/V0 staged into LDS right after the unit-top barrier (LDS write overlaps the address math / zeroing) instead of just before the second barrier
# baseline (speedup 1.0000x reference)
; #define LAS __attribute__((address_space(3)))
; __device__ __forceinline__ void p_attn_sb(const Params& P, LAS unsigned char* lds) {
;     ...
;         const int qb = (L >> 8) & 7, bh = (L & 255) + 256 * (L >> 11), b = bh >> 4, h = bh & 15;
;         const size_t tokbase = (size_t)b * SEQ;
;         const h16* Kg = Kb + (size_t)bh * SEQ * DH; const h16* Vg = Vb + (size_t)bh * SEQ * DH;
;         const int t = 256 * qb + 32 * w + r;
;         const int nt = 4 * qb + 4;
;         __syncthreads();
;         if (tid < 16) flags[tid] = 0;
;         { const size_t go = (size_t)(64 * (nt - 1) + srow) * DH + sch * 8; const u32x4 k0 = *(const u32x4*)(Kg + go), v0 = *(const u32x4*)(Vg + go);
;           *(LAS u32x4*)(lds + A_K + srow * KP + sch * 16) = k0; *(LAS u32x4*)(lds + A_V + srow * KP + sch * 16) = v0; }
.LBB0_395:
	s_waitcnt vmcnt(8)
	s_barrier
	s_and_saveexec_b64 s[6:7], s[36:37]
	ds_write_b32 v174, v0 offset:40192
	s_or_b64 exec, exec, s[6:7]
	s_cmp_lg_u32 s81, 0
	s_cbranch_scc0 .Lsbpf_noearly
	ds_write_b128 v175, v[122:125]
	ds_write_b128 v175, v[126:129] offset:18432
.Lsbpf_noearly:
	s_bfe_u32 s6, s20, 0x30008
	s_ashr_i32 s7, s20, 3
	s_lshl_b32 s25, s6, 8
	s_lshl_b32 s24, s6, 2
	s_and_b32 s6, s20, 0xff
	s_and_b32 s7, s7, 0xffffff00
	s_or_b32 s6, s7, s6
	s_ashr_i32 s14, s6, 4
	s_ashr_i32 s7, s6, 31
	s_ashr_i32 s15, s14, 31
	s_lshl_b64 s[8:9], s[6:7], 18
	v_readlane_b32 s6, v254, 18
	s_add_u32 s6, s6, s8
	v_readlane_b32 s7, v254, 19
	v_add_u32_e32 v1, s25, v165
	s_addc_u32 s7, s7, s9
	v_readlane_b32 s12, v254, 16
	v_add_u32_e32 v2, 0xc0, v1
	s_add_u32 s8, s12, s8
	v_readlane_b32 s12, v254, 17
	v_ashrrev_i32_e32 v3, 31, v2
	s_addc_u32 s9, s12, s9
	s_add_i32 s26, s25, s10
	v_lshlrev_b64 v[2:3], 7, v[2:3]
	v_or_b32_e32 v170, s26, v163
	v_lshl_or_b32 v2, v164, 1, v2
	v_lshl_add_u64 v[4:5], s[6:7], 0, v[2:3]
	v_lshl_add_u64 v[2:3], s[8:9], 0, v[2:3]
	v_ashrrev_i32_e32 v171, 31, v170
	s_cmp_lg_u32 s81, 0
	s_cbranch_scc1 .Lsbpf_a
	global_load_dwordx4 v[122:125], v[4:5], off
	global_load_dwordx4 v[126:129], v[2:3], off

; #define LAS __attribute__((address_space(3)))
; __device__ __forceinline__ void p_attn_sb(const Params& P, LAS unsigned char* lds) {
;     ...
;           *(LAS u32x4*)(lds + A_K + srow * KP + sch * 16) = k0; *(LAS u32x4*)(lds + A_V + srow * KP + sch * 16) = v0; }
;         h16x8 qf[4];
;         { const h16* qp = Qb + (tokbase + t) * DM + h * DH + 8 * hh;
; #pragma unroll
;           for (int ks = 0; ks < 4; ++ks) qf[ks] = *(const h16x8*)(qp + 16 * ks); }
;         __syncthreads();
;         float carry = 0.f; bool wdone = false; f32x16 o[2];
; #pragma unroll
;         for (int i = 0; i < 16; ++i) { o[0][i] = 0.f; o[1][i] = 0.f; }
.Lsbpf_b:
	v_mov_b32_e32 v14, v0
	v_mov_b32_e32 v15, v0
	v_mov_b32_e32 v1, v0
	v_mov_b32_e32 v2, v0
	v_mov_b32_e32 v3, v0
	v_mov_b32_e32 v4, v0
	v_mov_b32_e32 v5, v0
	v_mov_b32_e32 v6, v0
	v_mov_b32_e32 v7, v0
	v_mov_b32_e32 v8, v0
	v_mov_b32_e32 v9, v0
	v_mov_b32_e32 v10, v0
	v_mov_b32_e32 v11, v0
	v_mov_b32_e32 v12, v0
	v_mov_b32_e32 v13, v0
	v_mov_b64_e32 v[48:49], v[14:15]
	s_mov_b32 s28, 3
	s_mov_b32 s33, 1
	s_mov_b32 s29, 6
	s_add_i32 s40, s24, 4
	v_mov_b32_e32 v167, 0
	s_mov_b64 s[16:17], 0
	v_mov_b64_e32 v[46:47], v[12:13]
	v_mov_b64_e32 v[44:45], v[10:11]
	v_mov_b64_e32 v[42:43], v[8:9]
	v_mov_b64_e32 v[40:41], v[6:7]
	v_mov_b64_e32 v[38:39], v[4:5]
	v_mov_b64_e32 v[36:37], v[2:3]
	v_mov_b64_e32 v[34:35], v[0:1]
	s_cmp_lg_u32 s81, 0
	s_cbranch_scc1 .Lsbpf_nolate
	s_waitcnt vmcnt(5)
	ds_write_b128 v175, v[122:125]
	s_waitcnt vmcnt(4)
	ds_write_b128 v175, v[126:129] offset:18432
.Lsbpf_nolate:
	v_mov_b64_e32 v[32:33], v[14:15]
	v_mov_b64_e32 v[30:31], v[12:13]
	v_mov_b64_e32 v[28:29], v[10:11]
	v_mov_b64_e32 v[26:27], v[8:9]
	v_mov_b64_e32 v[24:25], v[6:7]
	v_mov_b64_e32 v[22:23], v[4:5]
	v_mov_b64_e32 v[20:21], v[2:3]
	v_mov_b64_e32 v[18:19], v[0:1]
	s_waitcnt lgkmcnt(0)
	s_barrier
	s_branch .LBB0_399
